# all FFN weight conversion tiles moved into phase F idle round; none in phase E
# baseline (speedup 1.0000x reference)
; #define FFN_CONVERT(t0, t1) do { if (bx >= 32) { \
;         const FfnCtx fc{a.in[20] + (size_t)l * 2048 * DFF, a.in[21] + (size_t)l * 2048 * DFF, a.in[22] + (size_t)l * DFF * 2048, WGU, WDOWN}; \
;         transpose_run<SelFfn>(lds, fc, (t0) + bx - 32, (t1), G - 32); } } while (0)
; __global__ void __launch_bounds__(NTHREADS, 2) mega_fwd(Args a) {
;     ...
;             FFN_CONVERT(0, 1056);
.LBB0_841:
	s_cmp_lt_i32 s33, 32
	s_cbranch_scc1 .LBB0_913
.LBB0_913:
	s_add_i32 s0, s58, 5
	s_cmp_ge_i32 s0, s25
	s_cbranch_scc1 .LBB0_981
	v_readlane_b32 s34, v253, 40
	v_readlane_b32 s35, v253, 41
	s_mov_b64 s[28:29], -1
	s_and_b64 vcc, exec, s[34:35]
	s_cbranch_vccz .LBB0_968
	s_waitcnt vmcnt(0)
	s_waitcnt vmcnt(0) lgkmcnt(0)
	s_barrier
	s_mov_b64 s[28:29], exec
	v_readlane_b32 s34, v253, 2
	v_readlane_b32 s35, v253, 3
	s_and_b64 s[34:35], s[28:29], s[34:35]
	s_mov_b64 exec, s[34:35]
	s_cbranch_execz .LBB0_967
	s_add_i32 s2, 0, 0x20000
	v_mov_b32_e32 v0, s2
	s_waitcnt vmcnt(0) expcnt(0) lgkmcnt(0)
	ds_read_b32 v2, v0
	v_readlane_b32 s4, v254, 49
	s_waitcnt lgkmcnt(0)
	v_cmp_ne_u32_e32 vcc, 0, v2
	v_mov_b32_e32 v0, s4
	ds_read_b32 v0, v0
	v_readlane_b32 s4, v253, 42
	s_cbranch_vccnz .LBB0_931
	s_mov_b32 s31, 1
	s_branch .LBB0_919

; #define LAS __attribute__((address_space(3)))
; __device__ __forceinline__ int tid_l() { int t = threadIdx.x; asm volatile("" : "+v"(t)); return t; }
; __device__ __forceinline__ unsigned cvt_pk_bf16(float lo, float hi) { unsigned r; asm("v_cvt_pk_bf16_f32 %0, %1, %2" : "=v"(r) : "v"(lo), "v"(hi)); return r; }
; #define FFN_CONVERT(t0, t1) do { if (bx >= 32) { \
;         const FfnCtx fc{a.in[20] + (size_t)l * 2048 * DFF, a.in[21] + (size_t)l * 2048 * DFF, a.in[22] + (size_t)l * DFF * 2048, WGU, WDOWN}; \
;         transpose_run<SelFfn>(lds, fc, (t0) + bx - 32, (t1), G - 32); } } while (0)
; template <class SEL, class CTX>
; __device__ __forceinline__ void transpose_run(LAS unsigned char* lds, const CTX& ctx, int t0, int t1, int stride) {
;     const int tid = tid_l();
;     LAS unsigned* tl = (LAS unsigned*)lds;
;     const int k = tid >> 3, n8 = (tid & 7) * 8;
;     f32x4 v[4][2];
;     TrDesc d; int lt;
;     if (t0 < t1) { SEL::get(ctx, t0, d, lt); const int nkt = d.K >> 6, kt = lt % nkt, ct = lt / nkt;
;         const float* s = d.src + (size_t)(kt * 64 + k) * d.ldsrc + d.c0 + ct * 256 + n8;
; #pragma unroll
;         for (int q = 0; q < 4; ++q) { v[q][0] = *(const f32x4*)(s + q * 64); v[q][1] = *(const f32x4*)(s + q * 64 + 4); } }
;     for (int t = t0; t < t1; t += stride) {
;         SEL::get(ctx, t, d, lt);
;         const int nkt = d.K >> 6, kt = lt % nkt, ct = lt / nkt;
;         unsigned w[4][4];
; #pragma unroll
;         for (int q = 0; q < 4; ++q)
; #pragma unroll
;             for (int j = 0; j < 4; ++j) { const float lo = v[q][0][j], hi = v[q][1][j];
;                 const float recv = __shfl_xor((k & 1) ? lo : hi, 8);
;                 w[q][j] = (k & 1) ? cvt_pk_bf16(recv, hi) : cvt_pk_bf16(lo, recv); }
;         if (t + stride < t1) { TrDesc dn; int ltn; SEL::get(ctx, t + stride, dn, ltn); const int nktn = dn.K >> 6, ktn = ltn % nktn, ctn = ltn / nktn;
;             const float* s = dn.src + (size_t)(ktn * 64 + k) * dn.ldsrc + dn.c0 + ctn * 256 + n8;
; #pragma unroll
;             for (int q = 0; q < 4; ++q) { v[q][0] = *(const f32x4*)(s + q * 64); v[q][1] = *(const f32x4*)(s + q * 64 + 4); } }
; __global__ void __launch_bounds__(NTHREADS, 2) mega_fwd(Args a) {
;     ...
;             FFN_CONVERT(1056, 2112);
.LBB0_1000:
	s_cmp_lt_i32 s65, 32
	s_cbranch_scc1 .LBB0_1084
	v_writelane_b32 v255, s0, 24
	v_writelane_b32 v255, s2, 25
	v_writelane_b32 v255, s28, 26
	v_writelane_b32 v255, s29, 27
	v_writelane_b32 v255, s33, 28
	v_writelane_b32 v255, s34, 29
	v_writelane_b32 v255, s35, 30
	v_writelane_b32 v255, s36, 31
	v_writelane_b32 v255, s37, 32
	v_writelane_b32 v255, s38, 33
	v_writelane_b32 v255, s39, 34
	v_writelane_b32 v255, s40, 35
	v_writelane_b32 v255, s41, 36
	v_writelane_b32 v255, s44, 37
	v_writelane_b32 v255, s45, 38
	v_writelane_b32 v255, s46, 39
	v_writelane_b32 v255, s47, 44
	v_writelane_b32 v255, s48, 45
	v_writelane_b32 v255, s49, 46
	v_writelane_b32 v255, s50, 47
	v_writelane_b32 v255, s51, 48
	v_writelane_b32 v255, s52, 49
	v_writelane_b32 v255, s53, 50
	v_writelane_b32 v255, s54, 51
	v_writelane_b32 v255, s55, 52
	v_writelane_b32 v255, s56, 53
	v_writelane_b32 v255, s57, 54
	v_writelane_b32 v255, s58, 55
	v_writelane_b32 v255, s59, 56
	v_writelane_b32 v255, s90, 57
	v_writelane_b32 v255, vcc_lo, 58
	v_writelane_b32 v255, vcc_hi, 59
	s_sub_i32 s0, s65, 32
	s_add_i32 s0, s0, 0
	s_sub_i32 s2, s31, 32
	s_mul_i32 s28, s30, 0x2c00000
	v_readlane_b32 s44, v253, 28
	v_readlane_b32 s45, v253, 29
	v_readlane_b32 s46, v253, 30
	v_readlane_b32 s47, v253, 31
	v_readlane_b32 s48, v253, 32
	v_readlane_b32 s49, v253, 33
	s_nop 3
	s_add_u32 s44, s44, s28
	s_addc_u32 s45, s45, 0
	s_add_u32 s46, s46, s28
	s_addc_u32 s47, s47, 0
	s_add_u32 s48, s48, s28
	s_addc_u32 s49, s49, 0
	s_add_u32 s50, s22, 0x1650000
	s_addc_u32 s51, s23, 0
	s_add_u32 s52, s22, 0x4250000
	s_addc_u32 s53, s23, 0
	v_lshrrev_b32_e32 v100, 3, v175
	v_and_b32_e32 v96, 7, v175
	v_lshlrev_b32_e32 v101, 5, v96
	v_and_b32_e32 v97, 1, v100
	v_cmp_ne_u32_e32 vcc, 0, v97
	v_lshlrev_b32_e32 v98, 3, v96
	v_lshl_add_u32 v98, v97, 2, v98
	v_mul_u32_u24_e32 v98, 33, v98
	v_lshrrev_b32_e32 v99, 1, v100
	v_add_u32_e32 v98, v98, v99
	v_lshlrev_b32_e32 v102, 2, v98
	v_mul_u32_u24_e32 v98, 33, v100
	v_lshl_add_u32 v98, v96, 2, v98
	v_lshlrev_b32_e32 v103, 2, v98
	v_lshlrev_b32_e32 v99, 4, v96
	v_lshl_add_u32 v104, v100, 12, v99
	v_mul_u32_u24_e32 v98, 0x2c00, v100
	v_add_u32_e32 v105, v98, v99
	s_mov_b32 s33, s0
	s_cmpk_ge_u32 s33, 0x580
	s_cselect_b32 s34, 1, 0
	s_cmpk_ge_u32 s33, 0x2c0
	s_cselect_b32 s35, 1, 0
	s_add_i32 s36, s34, s35
	s_mul_i32 s36, s36, 0x2c0
	s_sub_i32 s36, s33, s36
	s_sub_i32 s35, s35, s34
	s_mul_hi_u32 s37, s36, 0x2e8ba2f
	s_mul_i32 s38, s37, 0x58
	s_sub_i32 s38, s36, s38
	s_lshr_b32 s39, s36, 5
	s_and_b32 s40, s36, 31
	s_cmp_eq_u32 s34, 1
	s_cselect_b32 s37, s37, s39
	s_cselect_b32 s38, s38, s40
	s_mov_b32 s58, 0x5800
	s_cselect_b32 s58, 0x2000, s58
	s_cselect_b32 s54, s48, s44
	s_cselect_b32 s55, s49, s45
	s_cmp_eq_u32 s35, 1
	s_cselect_b32 s54, s46, s54
	s_cselect_b32 s55, s47, s55
	s_lshl_b32 s39, s38, 6
	s_mul_i32 s39, s39, s58
	s_lshl_b32 s40, s37, 10
	s_add_u32 s39, s39, s40
	s_add_u32 s54, s54, s39
	s_addc_u32 s55, s55, 0
	v_mad_u32_u24 v106, v100, s58, v101
	global_load_dwordx4 v[0:3], v106, s[54:55]
	global_load_dwordx4 v[4:7], v106, s[54:55] offset:16
	global_load_dwordx4 v[8:11], v106, s[54:55] offset:256
	global_load_dwordx4 v[12:15], v106, s[54:55] offset:272
	global_load_dwordx4 v[16:19], v106, s[54:55] offset:512
	global_load_dwordx4 v[20:23], v106, s[54:55] offset:528
	global_load_dwordx4 v[24:27], v106, s[54:55] offset:768
	global_load_dwordx4 v[28:31], v106, s[54:55] offset:784
